# prep_pass row loop: all row loads issued together at the top of the iteration, loop-invariant gain/table loads hoisted out; MLP-up epilogue loads one 16-B piece per lane (permlane16/32 reduce)
# speedup vs baseline: 1.0645x; 1.0163x over previous
.LBB0_294:
	s_lshl_b32 s6, s69, 3
	s_add_i32 s44, s6, s70
	s_lshl_b32 s46, s68, 3
	s_cmp_gt_i32 s44, 0xffff
	v_ashrrev_i32_e32 v27, 31, v26
	s_cbranch_scc1 .LBB0_336
	s_mul_i32 s22, s40, 0xc0
	s_lshl_b64 s[6:7], s[22:23], 2
	s_waitcnt lgkmcnt(0)
	s_add_u32 s4, s4, s6
	s_addc_u32 s5, s5, s7
	s_lshl_b32 s22, s40, 7
	s_lshl_b64 s[6:7], s[22:23], 2
	s_add_u32 s6, s2, s6
	s_addc_u32 s7, s3, s7
	s_getpc_b64 s[8:9]
	s_add_u32 s8, s8, _ZN3pg88ROPE_INVE@rel32@lo+4
	s_addc_u32 s9, s9, _ZN3pg88ROPE_INVE@rel32@hi+12
	s_cmp_lg_u32 s40, 0
	v_cmp_gt_i32_e64 s[2:3], 48, v26
	s_cselect_b64 s[12:13], -1, 0
	v_lshl_add_u64 v[12:13], v[26:27], 2, s[8:9]
	v_cmp_gt_i32_e64 s[8:9], 40, v26
	s_and_b64 s[12:13], s[12:13], s[2:3]
	s_ashr_i32 s45, s44, 31
	s_ashr_i32 s47, s46, 31
	v_lshlrev_b32_e32 v2, 2, v26
	s_or_b64 s[50:51], s[8:9], s[12:13]
	s_lshl_b64 s[20:21], s[44:45], 6
	s_lshl_b64 s[52:53], s[46:47], 6
	s_lshl_b64 s[54:55], s[44:45], 2
	v_ashrrev_i32_e32 v3, 31, v2
	s_add_u32 s54, s16, s54
	v_xor_b32_e32 v34, 64, v2
	v_xor_b32_e32 v35, 0x80, v2
	v_lshlrev_b64 v[4:5], 2, v[2:3]
	v_add_u32_e32 v0, 0xffffff60, v2
	s_addc_u32 s55, s17, s55
	s_lshl_b64 s[16:17], s[44:45], 9
	v_lshlrev_b64 v[2:3], 1, v[2:3]
	s_lshl_b64 s[56:57], s[46:47], 2
	v_lshl_add_u64 v[20:21], s[16:17], 0, v[2:3]
	s_lshl_b64 s[58:59], s[46:47], 9
	s_lshl_b64 s[16:17], s[44:45], 8
	v_lshl_add_u64 v[8:9], s[4:5], 0, v[4:5]
	v_lshl_add_u64 v[10:11], s[6:7], 0, v[4:5]
	v_lshl_add_u64 v[4:5], s[10:11], 0, v[4:5]
	s_mov_b64 s[10:11], 0x1800
	s_add_u32 s16, s16, 0x22000000
	v_lshl_add_u64 v[14:15], v[4:5], 0, s[10:11]
	v_add_u32_e32 v4, -16, v26
	s_addc_u32 s17, s17, 0
	v_cmp_gt_u32_e64 s[12:13], 24, v4
	v_lshlrev_b64 v[4:5], 1, v[26:27]
	v_lshl_add_u64 v[22:23], s[16:17], 0, v[2:3]
	s_lshl_b64 s[16:17], s[44:45], 12
	v_cmp_gt_i32_e64 s[4:5], 32, v26
	v_cmp_gt_i32_e64 s[6:7], 16, v26
	v_cmp_lt_i32_e64 s[10:11], 7, v26
	v_lshl_add_u64 v[16:17], s[20:21], 0, v[4:5]
	v_lshl_add_u64 v[18:19], v[0:1], 1, s[20:21]
	s_lshl_b64 s[60:61], s[46:47], 8
	v_lshl_add_u64 v[24:25], s[16:17], 0, v[2:3]
	s_lshl_b64 s[62:63], s[46:47], 12
	v_lshl_add_u64 v[28:29], s[16:17], 0, v[4:5]
	s_mov_b32 s22, s44
	s_mov_b64 exec, s[2:3]
	global_load_dwordx4 v[88:91], v[8:9], off
	s_mov_b64 exec, s[4:5]
	global_load_dwordx4 v[92:95], v[10:11], off
	s_mov_b64 exec, s[6:7]
	global_load_dword v96, v[12:13], off
	s_mov_b64 exec, s[50:51]
	global_load_dwordx4 v[100:103], v[14:15], off
	s_mov_b64 exec, -1
	s_waitcnt vmcnt(0)
	v_mov_b32_e32 v124, v93
	v_mov_b32_e32 v125, v95
	v_mov_b32_e32 v126, v92
	v_mov_b32_e32 v127, v94
	s_branch .LBB0_298

.LBB0_298:
	s_waitcnt lgkmcnt(0)
	v_mov_b32_e32 v32, 0
	v_lshl_add_u64 v[2:3], s[48:49], 0, v[24:25]
	s_mov_b64 s[100:101], 0x10000000
	v_lshl_add_u64 v[116:117], v[2:3], 0, s[100:101]
	v_lshl_add_u64 v[118:119], s[48:49], 0, v[28:29]
	v_lshl_add_u64 v[118:119], v[118:119], 0, s[100:101]
	s_mov_b64 exec, s[2:3]
	global_load_dwordx2 v[104:105], v[116:117], off
	s_mov_b64 exec, s[4:5]
	global_load_dwordx2 v[106:107], v[116:117], off offset:384
	s_mov_b64 exec, s[6:7]
	global_load_dword v108, v1, s[54:55]
	global_load_ushort v109, v[118:119], off offset:640
	global_load_ushort v110, v[118:119], off offset:672
	s_mov_b64 exec, s[50:51]
	s_mov_b64 s[100:101], 0x10000ec0
	v_lshl_add_u64 v[120:121], v[2:3], 0, s[100:101]
	v_lshl_add_u64 v[118:119], s[48:49], 0, v[18:19]
	s_mov_b64 s[100:101], 0x25000000
	v_lshl_add_u64 v[122:123], v[118:119], 0, s[100:101]
	v_cndmask_b32_e64 v121, v123, v121, s[8:9]
	v_cndmask_b32_e64 v120, v122, v120, s[8:9]
	global_load_dwordx2 v[112:113], v[120:121], off
	s_and_b32 s100, s22, 0xfff
	s_cmp_eq_u32 s100, 0
	s_cbranch_scc1 .Lprep_noprev
	s_mov_b64 s[100:101], 0xffffec0
	v_lshl_add_u64 v[120:121], v[2:3], 0, s[100:101]
	s_mov_b64 s[100:101], 0x24ffffc0
	v_lshl_add_u64 v[122:123], v[118:119], 0, s[100:101]
	v_cndmask_b32_e64 v121, v123, v121, s[8:9]
	v_cndmask_b32_e64 v120, v122, v120, s[8:9]
	global_load_dwordx2 v[114:115], v[120:121], off
.Lprep_noprev:
	s_mov_b64 exec, -1
	s_waitcnt vmcnt(0)
	v_mov_b32_e32 v0, 0
	v_mov_b32_e32 v7, 0
	v_mov_b32_e32 v5, 0
	v_mov_b32_e32 v6, 0
	v_mov_b32_e32 v4, 0
	s_and_saveexec_b64 s[16:17], s[2:3]
	s_cbranch_execz .LBB0_300
	v_add_co_u32_e32 v4, vcc, 0x10000000, v2
	s_nop 1
	v_addc_co_u32_e32 v5, vcc, 0, v3, vcc
	v_and_b32_e32 v4, 0xffff0000, v104
	v_and_b32_e32 v5, 0xffff0000, v105
	v_lshlrev_b32_e32 v6, 16, v104
	v_lshlrev_b32_e32 v7, 16, v105
	v_pk_mul_f32 v[30:31], v[4:5], v[4:5]
	s_nop 0
	v_pk_fma_f32 v[30:31], v[6:7], v[6:7], v[30:31]
	s_nop 0
	v_add_f32_e32 v0, v30, v31
.LBB0_300:
	s_or_b64 exec, exec, s[16:17]
	s_nop 0
	v_add_f32_dpp v0, v0, v0 quad_perm:[1,0,3,2] row_mask:0xf bank_mask:0xf bound_ctrl:1
	v_mov_b32_e32 v33, 0
	s_nop 0
	v_add_f32_dpp v0, v0, v0 quad_perm:[2,3,0,1] row_mask:0xf bank_mask:0xf bound_ctrl:1
	s_nop 1
	v_add_f32_dpp v0, v0, v0 row_half_mirror row_mask:0xf bank_mask:0xf bound_ctrl:1
	s_nop 1
	v_add_f32_dpp v0, v0, v0 row_mirror row_mask:0xf bank_mask:0xf bound_ctrl:1
	ds_bpermute_b32 v30, v34, v0
	s_waitcnt lgkmcnt(0)
	v_add_f32_e32 v0, v0, v30
	ds_bpermute_b32 v30, v35, v0
	s_and_saveexec_b64 s[64:65], s[2:3]
	s_cbranch_execz .LBB0_302
	s_waitcnt lgkmcnt(0)
	v_add_f32_e32 v0, v0, v30
	v_fmamk_f32 v0, v0, 0x3baaaaab, v212
	v_mul_f32_e32 v30, 0x4f800000, v0
	v_cmp_gt_f32_e32 vcc, s74, v0
	v_mov_b32_e32 v31, v4
	s_nop 0
	v_cndmask_b32_e32 v0, v0, v30, vcc
	v_sqrt_f32_e32 v32, v0
	v_mov_b32_e32 v30, v6
	v_add_u32_e32 v4, -1, v32
	v_add_u32_e32 v6, 1, v32
	v_fma_f32 v33, -v4, v32, v0
	v_fma_f32 v40, -v6, v32, v0
	v_cmp_ge_f32_e64 s[16:17], 0, v33
	s_nop 1
	v_cndmask_b32_e64 v4, v32, v4, s[16:17]
	v_cmp_lt_f32_e64 s[16:17], 0, v40
	s_nop 1
	v_cndmask_b32_e64 v4, v4, v6, s[16:17]
	v_mul_f32_e32 v6, 0x37800000, v4
	v_cndmask_b32_e32 v4, v4, v6, vcc
	v_cmp_class_f32_e32 vcc, v0, v213
	s_nop 1
	v_cndmask_b32_e32 v0, v4, v0, vcc
	v_div_scale_f32 v6, s[16:17], v0, v0, 1.0
	v_rcp_f32_e32 v32, v6
	v_mov_b32_e32 v4, v7
	v_div_scale_f32 v7, vcc, 1.0, v0, 1.0
	v_fma_f32 v33, -v6, v32, 1.0
	v_fmac_f32_e32 v32, v33, v32
	v_mul_f32_e32 v33, v7, v32
	v_fma_f32 v40, -v6, v33, v7
	v_fmac_f32_e32 v33, v40, v32
	v_fma_f32 v6, -v6, v33, v7
	v_div_fmas_f32 v6, v6, v32, v33
	v_div_fixup_f32 v0, v6, v0, 1.0
	v_pk_mul_f32 v[6:7], v[30:31], v[0:1] op_sel_hi:[1, 0]
	v_pk_mul_f32 v[4:5], v[4:5], v[0:1] op_sel_hi:[1, 0]
	v_pk_mul_f32 v[6:7], v[6:7], v[88:89]
	v_pk_mul_f32 v[4:5], v[4:5], v[90:91]
	v_and_b32_sdwa v30, v6, v254 dst_sel:DWORD dst_unused:UNUSED_PAD src0_sel:WORD_1 src1_sel:DWORD
	v_and_b32_sdwa v32, v4, v254 dst_sel:DWORD dst_unused:UNUSED_PAD src0_sel:WORD_1 src1_sel:DWORD
	v_and_b32_sdwa v0, v7, v254 dst_sel:DWORD dst_unused:UNUSED_PAD src0_sel:WORD_1 src1_sel:DWORD
	v_and_b32_sdwa v31, v5, v254 dst_sel:DWORD dst_unused:UNUSED_PAD src0_sel:WORD_1 src1_sel:DWORD
	v_add3_u32 v6, v6, v30, s80
	v_add3_u32 v4, v4, v32, s80
	v_add3_u32 v0, v7, v0, s80
	v_add3_u32 v5, v5, v31, s80
	v_lshrrev_b32_e32 v6, 16, v6
	v_lshrrev_b32_e32 v4, 16, v4
	v_and_or_b32 v32, v0, s79, v6
	v_and_or_b32 v33, v5, s79, v4
.LBB0_302:
	s_or_b64 exec, exec, s[64:65]
	s_waitcnt lgkmcnt(0)
	v_lshl_add_u64 v[30:31], s[48:49], 0, v[20:21]
	v_add_co_u32_e32 v4, vcc, 0x20000000, v30
	v_mov_b32_e32 v0, 0
	s_nop 0
	v_addc_co_u32_e32 v5, vcc, 0, v31, vcc
	global_store_dwordx2 v[4:5], v[32:33], off
	v_mov_b32_e32 v4, 0
	v_mov_b32_e32 v5, 0
	v_mov_b32_e32 v6, 0
	v_mov_b32_e32 v7, 0
	s_and_saveexec_b64 s[16:17], s[4:5]
	s_cbranch_execz .LBB0_304
	v_add_co_u32_e32 v4, vcc, 0x10000000, v2
	s_nop 1
	v_addc_co_u32_e32 v5, vcc, 0, v3, vcc
	v_lshlrev_b32_e32 v7, 16, v107
	v_lshlrev_b32_e32 v6, 16, v106
	v_and_b32_e32 v5, 0xffff0000, v107
	v_and_b32_e32 v4, 0xffff0000, v106
	v_pk_mul_f32 v[32:33], v[4:5], v[4:5]
	s_nop 0
	v_pk_fma_f32 v[32:33], v[6:7], v[6:7], v[32:33]
	s_nop 0
	v_add_f32_e32 v0, v32, v33
.LBB0_304:
	s_or_b64 exec, exec, s[16:17]
	s_nop 0
	v_add_f32_dpp v0, v0, v0 quad_perm:[1, 0, 3, 2] row_mask:0xf bank_mask:0xf bound_ctrl:1
	s_nop 1
	v_add_f32_dpp v0, v0, v0 quad_perm:[2, 3, 0, 1] row_mask:0xf bank_mask:0xf bound_ctrl:1
	s_nop 1
	v_add_f32_dpp v0, v0, v0 row_half_mirror row_mask:0xf bank_mask:0xf bound_ctrl:1
	s_nop 1
	v_add_f32_dpp v0, v0, v0 row_mirror row_mask:0xf bank_mask:0xf bound_ctrl:1
	ds_bpermute_b32 v32, v34, v0
	s_waitcnt lgkmcnt(0)
	v_add_f32_e32 v0, v0, v32
	ds_bpermute_b32 v32, v35, v0
	s_and_saveexec_b64 s[64:65], s[4:5]
	s_cbranch_execz .LBB0_306
	s_waitcnt lgkmcnt(0)
	v_add_f32_e32 v0, v0, v32
	v_fmamk_f32 v0, v0, 0x3c000000, v212
	v_mul_f32_e32 v32, 0x4f800000, v0
	v_cmp_gt_f32_e32 vcc, s74, v0
	s_nop 1
	v_cndmask_b32_e32 v0, v0, v32, vcc
	v_sqrt_f32_e32 v32, v0
	s_nop 0
	v_add_u32_e32 v33, -1, v32
	v_add_u32_e32 v40, 1, v32
	v_fma_f32 v41, -v33, v32, v0
	v_fma_f32 v42, -v40, v32, v0
	v_cmp_ge_f32_e64 s[16:17], 0, v41
	s_nop 1
	v_cndmask_b32_e64 v32, v32, v33, s[16:17]
	v_cmp_lt_f32_e64 s[16:17], 0, v42
	s_nop 1
	v_cndmask_b32_e64 v32, v32, v40, s[16:17]
	v_mul_f32_e32 v33, 0x37800000, v32
	v_cndmask_b32_e32 v32, v32, v33, vcc
	v_cmp_class_f32_e32 vcc, v0, v213
	s_nop 1
	v_cndmask_b32_e32 v0, v32, v0, vcc
	v_div_scale_f32 v32, s[16:17], v0, v0, 1.0
	v_rcp_f32_e32 v33, v32
	v_div_scale_f32 v40, vcc, 1.0, v0, 1.0
	v_fma_f32 v41, -v32, v33, 1.0
	v_fmac_f32_e32 v33, v41, v33
	v_mul_f32_e32 v41, v40, v33
	v_fma_f32 v42, -v32, v41, v40
	v_fmac_f32_e32 v41, v42, v33
	v_fma_f32 v32, -v32, v41, v40
	v_div_fmas_f32 v32, v32, v33, v41
	v_div_fixup_f32 v0, v32, v0, 1.0
	v_pk_mul_f32 v[4:5], v[4:5], v[0:1] op_sel_hi:[1, 0]
	v_pk_mul_f32 v[6:7], v[6:7], v[0:1] op_sel_hi:[1, 0]
	v_pk_mul_f32 v[4:5], v[4:5], v[124:125]
	v_pk_mul_f32 v[6:7], v[6:7], v[126:127]
	v_and_b32_sdwa v33, v5, v254 dst_sel:DWORD dst_unused:UNUSED_PAD src0_sel:WORD_1 src1_sel:DWORD
	v_and_b32_sdwa v36, v4, v254 dst_sel:DWORD dst_unused:UNUSED_PAD src0_sel:WORD_1 src1_sel:DWORD
	v_and_b32_sdwa v0, v7, v254 dst_sel:DWORD dst_unused:UNUSED_PAD src0_sel:WORD_1 src1_sel:DWORD
	v_and_b32_sdwa v32, v6, v254 dst_sel:DWORD dst_unused:UNUSED_PAD src0_sel:WORD_1 src1_sel:DWORD
	v_add3_u32 v5, v5, v33, s80
	v_add3_u32 v4, v4, v36, s80
	v_add3_u32 v6, v6, v32, s80
	v_add3_u32 v0, v7, v0, s80
	v_and_b32_e32 v5, 0xffff0000, v5
	v_and_b32_e32 v4, 0xffff0000, v4
	v_or_b32_sdwa v5, v5, v0 dst_sel:DWORD dst_unused:UNUSED_PAD src0_sel:DWORD src1_sel:WORD_1
	v_or_b32_sdwa v4, v4, v6 dst_sel:DWORD dst_unused:UNUSED_PAD src0_sel:DWORD src1_sel:WORD_1
	v_lshl_add_u64 v[6:7], s[48:49], 0, v[22:23]
	global_store_dwordx2 v[6:7], v[4:5], off
.LBB0_306:
	s_or_b64 exec, exec, s[64:65]
	s_and_saveexec_b64 s[16:17], s[6:7]
	s_cbranch_execz .LBB0_308
	s_waitcnt lgkmcnt(0)
	v_lshl_add_u64 v[4:5], s[48:49], 0, v[28:29]
	v_add_co_u32_e32 v4, vcc, 0x10000000, v4
	v_cvt_f64_i32_e32 v[6:7], v108
	v_addc_co_u32_e32 v5, vcc, 0, v5, vcc
	v_cvt_f64_f32_e32 v[32:33], v96
	v_mul_f64 v[6:7], v[6:7], v[32:33]
	v_mul_f64 v[32:33], v[6:7], s[30:31]
	v_rndne_f64_e32 v[32:33], v[32:33]
	v_fma_f64 v[6:7], v[6:7], s[30:31], -v[32:33]
	v_cvt_f32_f64_e32 v0, v[6:7]
	v_sin_f32_e32 v6, v0
	v_cos_f32_e32 v0, v0
	v_lshl_add_u64 v[4:5], s[48:49], 0, v[16:17]
	v_add_co_u32_e32 v4, vcc, 0x3b00000, v4
	v_lshlrev_b32_e32 v7, 16, v109
	v_lshlrev_b32_e32 v32, 16, v110
	v_mul_f32_e32 v33, v6, v32
	v_mul_f32_e32 v32, v0, v32
	v_fma_f32 v0, v0, v7, -v33
	v_fmac_f32_e32 v32, v6, v7
	v_bfe_u32 v6, v0, 16, 1
	v_addc_co_u32_e32 v5, vcc, 0, v5, vcc
	v_bfe_u32 v7, v32, 16, 1
	v_add3_u32 v0, v0, v6, s80
	v_add3_u32 v6, v32, v7, s80
	global_store_short_d16_hi v[4:5], v0, off
	global_store_short_d16_hi v[4:5], v6, off offset:32
.LBB0_308:
	s_or_b64 exec, exec, s[16:17]
	v_mov_b32_e32 v5, 0
	v_mov_b32_e32 v4, 0
	s_and_saveexec_b64 s[16:17], s[50:51]
	s_cbranch_execz .LBB0_297
	s_mov_b64 s[20:21], 0x10000ec0
	v_lshl_add_u64 v[6:7], v[2:3], 0, s[20:21]
	v_lshl_add_u64 v[4:5], s[48:49], 0, v[18:19]
	s_mov_b64 s[20:21], 0x25000000
	s_waitcnt lgkmcnt(0)
	v_lshl_add_u64 v[32:33], v[4:5], 0, s[20:21]
	v_cndmask_b32_e64 v7, v33, v7, s[8:9]
	v_cndmask_b32_e64 v6, v32, v6, s[8:9]
	s_and_b32 s20, s22, 0xfff
	s_cmp_eq_u32 s20, 0
	s_cbranch_scc1 .LBB0_311
	s_mov_b64 s[20:21], 0xffffec0
	v_lshl_add_u64 v[2:3], v[2:3], 0, s[20:21]
	s_mov_b64 s[20:21], 0x24ffffc0
	v_lshl_add_u64 v[4:5], v[4:5], 0, s[20:21]
	v_cndmask_b32_e64 v3, v5, v3, s[8:9]
	v_cndmask_b32_e64 v2, v4, v2, s[8:9]
	v_lshlrev_b32_e32 v7, 16, v114
	v_and_b32_e32 v37, 0xffff0000, v114
	v_lshlrev_b32_e32 v36, 16, v115
	v_and_b32_e32 v6, 0xffff0000, v115
	s_branch .LBB0_312

.LBB0_312:
	v_lshlrev_b32_e32 v0, 16, v112
	v_sub_f32_e32 v7, v7, v0
	v_fmac_f32_e32 v0, v100, v7
	s_and_saveexec_b64 s[20:21], s[10:11]
	s_xor_b64 s[64:65], exec, s[20:21]
	s_cbranch_execz .LBB0_316
	s_and_saveexec_b64 s[66:67], s[12:13]
	s_cbranch_execz .LBB0_315
	v_mul_f32_e32 v0, 0xbfb8aa3b, v0
	v_exp_f32_e32 v0, v0
	s_nop 0
	v_add_f32_e32 v0, 1.0, v0
	v_div_scale_f32 v2, s[20:21], v0, v0, 1.0
	v_rcp_f32_e32 v7, v2
	v_div_scale_f32 v38, vcc, 1.0, v0, 1.0
	v_fma_f32 v39, -v2, v7, 1.0
	v_fmac_f32_e32 v7, v39, v7
	v_mul_f32_e32 v39, v38, v7
	v_fma_f32 v40, -v2, v39, v38
	v_fmac_f32_e32 v39, v40, v7
	v_fma_f32 v2, -v2, v39, v38
	v_div_fmas_f32 v2, v2, v7, v39
	v_div_fixup_f32 v0, v2, v0, 1.0

.LBB0_318:
	s_or_b64 exec, exec, s[64:65]
	v_and_b32_e32 v7, 0xffff0000, v112
	v_sub_f32_e32 v2, v37, v7
	v_fmac_f32_e32 v7, v101, v2
	s_and_saveexec_b64 s[20:21], s[10:11]
	s_xor_b64 s[64:65], exec, s[20:21]
	s_cbranch_execz .LBB0_322
	s_and_saveexec_b64 s[66:67], s[12:13]
	s_cbranch_execz .LBB0_321
	v_mul_f32_e32 v2, 0xbfb8aa3b, v7
	v_exp_f32_e32 v2, v2
	s_nop 0
	v_add_f32_e32 v2, 1.0, v2
	v_div_scale_f32 v3, s[20:21], v2, v2, 1.0
	v_rcp_f32_e32 v7, v3
	v_div_scale_f32 v32, vcc, 1.0, v2, 1.0
	v_fma_f32 v37, -v3, v7, 1.0
	v_fmac_f32_e32 v7, v37, v7
	v_mul_f32_e32 v37, v32, v7
	v_fma_f32 v38, -v3, v37, v32
	v_fmac_f32_e32 v37, v38, v7
	v_fma_f32 v3, -v3, v37, v32
	v_div_fmas_f32 v3, v3, v7, v37
	v_div_fixup_f32 v7, v3, v2, 1.0

.LBB0_324:
	s_or_b64 exec, exec, s[64:65]
	v_lshlrev_b32_e32 v2, 16, v113
	v_sub_f32_e32 v3, v36, v2
	v_fmac_f32_e32 v2, v102, v3
	s_and_saveexec_b64 s[20:21], s[10:11]
	s_xor_b64 s[64:65], exec, s[20:21]
	s_cbranch_execz .LBB0_328
	s_and_saveexec_b64 s[66:67], s[12:13]
	s_cbranch_execz .LBB0_327
	v_mul_f32_e32 v2, 0xbfb8aa3b, v2
	v_exp_f32_e32 v2, v2
	s_nop 0
	v_add_f32_e32 v2, 1.0, v2
	v_div_scale_f32 v3, s[20:21], v2, v2, 1.0
	v_rcp_f32_e32 v4, v3
	v_div_scale_f32 v32, vcc, 1.0, v2, 1.0
	v_fma_f32 v36, -v3, v4, 1.0
	v_fmac_f32_e32 v4, v36, v4
	v_mul_f32_e32 v36, v32, v4
	v_fma_f32 v37, -v3, v36, v32
	v_fmac_f32_e32 v36, v37, v4
	v_fma_f32 v3, -v3, v36, v32
	v_div_fmas_f32 v3, v3, v4, v36
	v_div_fixup_f32 v2, v3, v2, 1.0

.LBB0_330:
	s_or_b64 exec, exec, s[64:65]
	v_and_b32_e32 v3, 0xffff0000, v113
	v_sub_f32_e32 v4, v6, v3
	v_fmac_f32_e32 v3, v103, v4
	s_and_saveexec_b64 s[20:21], s[10:11]
	s_xor_b64 s[64:65], exec, s[20:21]
	s_cbranch_execz .LBB0_334
	s_and_saveexec_b64 s[66:67], s[12:13]
	s_cbranch_execz .LBB0_333
	v_mul_f32_e32 v3, 0xbfb8aa3b, v3
	v_exp_f32_e32 v3, v3
	s_nop 0
	v_add_f32_e32 v3, 1.0, v3
	v_div_scale_f32 v4, s[20:21], v3, v3, 1.0
	v_rcp_f32_e32 v5, v4
	v_div_scale_f32 v6, vcc, 1.0, v3, 1.0
	v_fma_f32 v32, -v4, v5, 1.0
	v_fmac_f32_e32 v5, v32, v5
	v_mul_f32_e32 v32, v6, v5
	v_fma_f32 v33, -v4, v32, v6
	v_fmac_f32_e32 v32, v33, v5
	v_fma_f32 v4, -v4, v32, v6
	v_div_fmas_f32 v4, v4, v5, v32
	v_div_fixup_f32 v3, v4, v3, 1.0

.LBB0_2431:
	v_lshl_add_u32 v142, s67, 8, v146
	v_ashrrev_i32_e32 v143, 31, v142
	v_lshlrev_b64 v[140:141], 6, v[142:143]
	v_lshl_add_u64 v[140:141], s[18:19], 0, v[140:141]
	v_mbcnt_lo_u32_b32 v252, -1, 0
	v_mbcnt_hi_u32_b32 v252, -1, v252
	v_and_b32_e32 v252, 0x30, v252
	v_mov_b32_e32 v253, 0
	v_lshl_add_u64 v[248:249], v[140:141], 0, v[252:253]
	s_mov_b64 s[100:101], 0x2000
	v_lshl_add_u64 v[250:251], v[248:249], 0, s[100:101]
	global_load_dwordx4 v[216:219], v[248:249], off
	global_load_dwordx4 v[220:223], v[248:249], off offset:1024
	s_waitcnt vmcnt(1)
	v_add_f32_e32 v216, v216, v217
	v_add_f32_e32 v218, v218, v219
	v_add_f32_e32 v216, v216, v218
	v_mov_b32_e32 v252, v216
	s_nop 1
	v_permlane16_swap_b32_e32 v252, v216
	v_add_f32_e32 v216, v216, v252
	v_mov_b32_e32 v252, v216
	s_nop 1
	v_permlane32_swap_b32_e32 v252, v216
	v_add_f32_e32 v140, v216, v252
	v_fmamk_f32 v140, v140, 0x3a800000, v212
	v_mul_f32_e32 v141, 0x4f800000, v140
	v_cmp_gt_f32_e32 vcc, s74, v140
	s_nop 1
	v_cndmask_b32_e32 v144, v140, v141, vcc
	v_sqrt_f32_e32 v145, v144
	v_lshl_or_b32 v140, s6, 8, v148
	v_cmp_gt_i32_e64 s[4:5], 2.0, v140
	v_ashrrev_i32_e32 v141, 31, v140
	v_add_u32_e32 v150, -1, v145
	v_add_u32_e32 v151, 1, v145
	v_fma_f32 v152, -v150, v145, v144
	v_fma_f32 v153, -v151, v145, v144
	v_cmp_ge_f32_e64 s[6:7], 0, v152
	s_nop 1
	v_cndmask_b32_e64 v145, v145, v150, s[6:7]
	v_cmp_lt_f32_e64 s[6:7], 0, v153
	s_nop 1
	v_cndmask_b32_e64 v145, v145, v151, s[6:7]
	v_mul_f32_e32 v150, 0x37800000, v145
	v_cndmask_b32_e32 v145, v145, v150, vcc
	v_cmp_class_f32_e32 vcc, v144, v213
	v_lshlrev_b64 v[150:151], 13, v[142:143]
	s_nop 0
	v_cndmask_b32_e32 v144, v145, v144, vcc
	v_div_scale_f32 v145, s[6:7], v144, v144, 1.0
	v_rcp_f32_e32 v152, v145
	v_div_scale_f32 v143, vcc, 1.0, v144, 1.0
	v_fma_f32 v153, -v145, v152, 1.0
	v_fmac_f32_e32 v152, v153, v152
	v_mul_f32_e32 v153, v143, v152
	v_fma_f32 v154, -v145, v153, v143
	v_fmac_f32_e32 v153, v154, v152
	v_fma_f32 v143, -v145, v153, v143
	v_div_fmas_f32 v143, v143, v152, v153
	v_div_fixup_f32 v144, v143, v144, 1.0
	v_pk_mul_f32 v[128:129], v[128:129], v[144:145] op_sel_hi:[1,0]
	v_pk_mul_f32 v[126:127], v[126:127], v[144:145] op_sel_hi:[1,0]
	v_pk_mul_f32 v[124:125], v[124:125], v[144:145] op_sel_hi:[1,0]
	v_pk_mul_f32 v[122:123], v[122:123], v[144:145] op_sel_hi:[1,0]
	v_max_f32_e32 v126, 0, v126
	v_max_f32_e32 v122, 0, v122
	v_max_f32_e32 v127, 0, v127
	v_max_f32_e32 v123, 0, v123
	v_max_f32_e32 v128, 0, v128
	v_max_f32_e32 v124, 0, v124
	v_max_f32_e32 v129, 0, v129
	v_max_f32_e32 v125, 0, v125
	v_mul_f32_e32 v126, v126, v126
	v_mul_f32_e32 v143, v122, v122
	v_mul_f32_e32 v122, v127, v127
	v_mul_f32_e32 v127, v123, v123
	v_mul_f32_e32 v123, v128, v128
	v_mul_f32_e32 v128, v124, v124
	v_mul_f32_e32 v124, v129, v129
	v_mul_f32_e32 v125, v125, v125
	v_cvt_pk_bf16_f32 v122, v126, v122
	v_cvt_pk_bf16_f32 v123, v123, v124
	v_cvt_pk_bf16_f32 v124, v143, v127
	v_lshl_add_u64 v[126:127], s[40:41], 0, v[150:151]
	v_cvt_pk_bf16_f32 v125, v128, v125
	s_and_saveexec_b64 s[6:7], s[4:5]
	s_cbranch_execz .LBB0_2433
	v_lshl_add_u64 v[128:129], v[140:141], 1, v[126:127]
	global_store_dwordx4 v[128:129], v[122:125], off nt

.LBB0_2435:
	s_or_b64 exec, exec, s[8:9]
	v_or_b32_e32 v144, 16, v142
	v_ashrrev_i32_e32 v145, 31, v144
	v_lshlrev_b64 v[114:115], 6, v[144:145]
	v_lshl_add_u64 v[126:127], s[18:19], 0, v[114:115]
	global_load_dwordx4 v[216:219], v[248:249], off offset:2048
	s_waitcnt vmcnt(3)
	v_add_f32_e32 v220, v220, v221
	v_add_f32_e32 v222, v222, v223
	v_add_f32_e32 v220, v220, v222
	v_mov_b32_e32 v252, v220
	s_nop 1
	v_permlane16_swap_b32_e32 v252, v220
	v_add_f32_e32 v220, v220, v252
	v_mov_b32_e32 v252, v220
	s_nop 1
	v_permlane32_swap_b32_e32 v252, v220
	v_add_f32_e32 v114, v220, v252
	v_fmamk_f32 v114, v114, 0x3a800000, v212
	v_mul_f32_e32 v115, 0x4f800000, v114
	v_cmp_gt_f32_e32 vcc, s74, v114
	s_nop 1
	v_cndmask_b32_e32 v114, v114, v115, vcc
	v_sqrt_f32_e32 v115, v114
	s_nop 0
	v_add_u32_e32 v116, -1, v115
	v_add_u32_e32 v117, 1, v115
	v_fma_f32 v118, -v116, v115, v114
	v_fma_f32 v119, -v117, v115, v114
	v_cmp_ge_f32_e64 s[8:9], 0, v118
	s_nop 1
	v_cndmask_b32_e64 v115, v115, v116, s[8:9]
	v_cmp_lt_f32_e64 s[8:9], 0, v119
	s_nop 1
	v_cndmask_b32_e64 v115, v115, v117, s[8:9]
	v_mul_f32_e32 v116, 0x37800000, v115
	v_cndmask_b32_e32 v115, v115, v116, vcc
	v_cmp_class_f32_e32 vcc, v114, v213
	v_lshlrev_b64 v[116:117], 13, v[144:145]
	s_nop 0
	v_cndmask_b32_e32 v114, v115, v114, vcc
	v_div_scale_f32 v115, s[8:9], v114, v114, 1.0
	v_rcp_f32_e32 v118, v115
	v_div_scale_f32 v119, vcc, 1.0, v114, 1.0
	v_fma_f32 v120, -v115, v118, 1.0
	v_fmac_f32_e32 v118, v120, v118
	v_mul_f32_e32 v120, v119, v118
	v_fma_f32 v121, -v115, v120, v119
	v_fmac_f32_e32 v120, v121, v118
	v_fma_f32 v115, -v115, v120, v119
	v_div_fmas_f32 v115, v115, v118, v120
	v_div_fixup_f32 v114, v115, v114, 1.0
	v_pk_mul_f32 v[112:113], v[112:113], v[114:115] op_sel_hi:[1,0]
	v_pk_mul_f32 v[110:111], v[110:111], v[114:115] op_sel_hi:[1,0]
	v_pk_mul_f32 v[108:109], v[108:109], v[114:115] op_sel_hi:[1,0]
	v_pk_mul_f32 v[106:107], v[106:107], v[114:115] op_sel_hi:[1,0]
	v_max_f32_e32 v110, 0, v110
	v_max_f32_e32 v106, 0, v106
	v_max_f32_e32 v111, 0, v111
	v_max_f32_e32 v107, 0, v107
	v_max_f32_e32 v112, 0, v112
	v_max_f32_e32 v108, 0, v108
	v_max_f32_e32 v113, 0, v113
	v_max_f32_e32 v109, 0, v109
	v_mul_f32_e32 v110, v110, v110
	v_mul_f32_e32 v115, v106, v106
	v_mul_f32_e32 v106, v111, v111
	v_mul_f32_e32 v111, v107, v107
	v_mul_f32_e32 v107, v112, v112
	v_mul_f32_e32 v112, v108, v108
	v_mul_f32_e32 v108, v113, v113
	v_mul_f32_e32 v109, v109, v109
	v_cvt_pk_bf16_f32 v106, v110, v106
	v_cvt_pk_bf16_f32 v107, v107, v108
	v_cvt_pk_bf16_f32 v108, v115, v111
	v_lshl_add_u64 v[110:111], s[40:41], 0, v[116:117]
	v_cvt_pk_bf16_f32 v109, v112, v109
	s_and_saveexec_b64 s[8:9], s[4:5]
	s_cbranch_execz .LBB0_2437
	v_lshl_add_u64 v[112:113], v[140:141], 1, v[110:111]
	global_store_dwordx4 v[112:113], v[106:109], off nt

.LBB0_2439:
	s_or_b64 exec, exec, s[8:9]
	v_or_b32_e32 v114, 32, v142
	v_ashrrev_i32_e32 v115, 31, v114
	v_lshlrev_b64 v[98:99], 6, v[114:115]
	v_lshl_add_u64 v[110:111], s[18:19], 0, v[98:99]
	global_load_dwordx4 v[220:223], v[248:249], off offset:3072
	s_waitcnt vmcnt(3)
	v_add_f32_e32 v216, v216, v217
	v_add_f32_e32 v218, v218, v219
	v_add_f32_e32 v216, v216, v218
	v_mov_b32_e32 v252, v216
	s_nop 1
	v_permlane16_swap_b32_e32 v252, v216
	v_add_f32_e32 v216, v216, v252
	v_mov_b32_e32 v252, v216
	s_nop 1
	v_permlane32_swap_b32_e32 v252, v216
	v_add_f32_e32 v98, v216, v252
	v_fmamk_f32 v98, v98, 0x3a800000, v212
	v_mul_f32_e32 v99, 0x4f800000, v98
	v_cmp_gt_f32_e32 vcc, s74, v98
	s_nop 1
	v_cndmask_b32_e32 v98, v98, v99, vcc
	v_sqrt_f32_e32 v99, v98
	s_nop 0
	v_add_u32_e32 v100, -1, v99
	v_add_u32_e32 v101, 1, v99
	v_fma_f32 v102, -v100, v99, v98
	v_fma_f32 v103, -v101, v99, v98
	v_cmp_ge_f32_e64 s[8:9], 0, v102
	s_nop 1
	v_cndmask_b32_e64 v99, v99, v100, s[8:9]
	v_cmp_lt_f32_e64 s[8:9], 0, v103
	s_nop 1
	v_cndmask_b32_e64 v99, v99, v101, s[8:9]
	v_mul_f32_e32 v100, 0x37800000, v99
	v_cndmask_b32_e32 v99, v99, v100, vcc
	v_cmp_class_f32_e32 vcc, v98, v213
	v_lshlrev_b64 v[100:101], 13, v[114:115]
	s_nop 0
	v_cndmask_b32_e32 v98, v99, v98, vcc
	v_div_scale_f32 v99, s[8:9], v98, v98, 1.0
	v_rcp_f32_e32 v102, v99
	v_div_scale_f32 v103, vcc, 1.0, v98, 1.0
	v_fma_f32 v104, -v99, v102, 1.0
	v_fmac_f32_e32 v102, v104, v102
	v_mul_f32_e32 v104, v103, v102
	v_fma_f32 v105, -v99, v104, v103
	v_fmac_f32_e32 v104, v105, v102
	v_fma_f32 v99, -v99, v104, v103
	v_div_fmas_f32 v99, v99, v102, v104
	v_div_fixup_f32 v98, v99, v98, 1.0
	v_pk_mul_f32 v[96:97], v[96:97], v[98:99] op_sel_hi:[1,0]
	v_pk_mul_f32 v[94:95], v[94:95], v[98:99] op_sel_hi:[1,0]
	v_pk_mul_f32 v[92:93], v[92:93], v[98:99] op_sel_hi:[1,0]
	v_pk_mul_f32 v[90:91], v[90:91], v[98:99] op_sel_hi:[1,0]
	v_max_f32_e32 v94, 0, v94
	v_max_f32_e32 v90, 0, v90
	v_max_f32_e32 v95, 0, v95
	v_max_f32_e32 v91, 0, v91
	v_max_f32_e32 v96, 0, v96
	v_max_f32_e32 v92, 0, v92
	v_max_f32_e32 v97, 0, v97
	v_max_f32_e32 v93, 0, v93
	v_mul_f32_e32 v94, v94, v94
	v_mul_f32_e32 v99, v90, v90
	v_mul_f32_e32 v90, v95, v95
	v_mul_f32_e32 v95, v91, v91
	v_mul_f32_e32 v91, v96, v96
	v_mul_f32_e32 v96, v92, v92
	v_mul_f32_e32 v92, v97, v97
	v_mul_f32_e32 v93, v93, v93
	v_cvt_pk_bf16_f32 v90, v94, v90
	v_cvt_pk_bf16_f32 v91, v91, v92
	v_cvt_pk_bf16_f32 v92, v99, v95
	v_lshl_add_u64 v[94:95], s[40:41], 0, v[100:101]
	v_cvt_pk_bf16_f32 v93, v96, v93
	s_and_saveexec_b64 s[8:9], s[4:5]
	s_cbranch_execz .LBB0_2441
	v_lshl_add_u64 v[96:97], v[140:141], 1, v[94:95]
	global_store_dwordx4 v[96:97], v[90:93], off nt

.LBB0_2443:
	s_or_b64 exec, exec, s[8:9]
	v_or_b32_e32 v98, 48, v142
	v_ashrrev_i32_e32 v99, 31, v98
	v_lshlrev_b64 v[82:83], 6, v[98:99]
	v_lshl_add_u64 v[94:95], s[18:19], 0, v[82:83]
	global_load_dwordx4 v[216:219], v[250:251], off
	s_waitcnt vmcnt(3)
	v_add_f32_e32 v220, v220, v221
	v_add_f32_e32 v222, v222, v223
	v_add_f32_e32 v220, v220, v222
	v_mov_b32_e32 v252, v220
	s_nop 1
	v_permlane16_swap_b32_e32 v252, v220
	v_add_f32_e32 v220, v220, v252
	v_mov_b32_e32 v252, v220
	s_nop 1
	v_permlane32_swap_b32_e32 v252, v220
	v_add_f32_e32 v82, v220, v252
	v_fmamk_f32 v82, v82, 0x3a800000, v212
	v_mul_f32_e32 v83, 0x4f800000, v82
	v_cmp_gt_f32_e32 vcc, s74, v82
	s_nop 1
	v_cndmask_b32_e32 v82, v82, v83, vcc
	v_sqrt_f32_e32 v83, v82
	s_nop 0
	v_add_u32_e32 v84, -1, v83
	v_add_u32_e32 v85, 1, v83
	v_fma_f32 v86, -v84, v83, v82
	v_fma_f32 v87, -v85, v83, v82
	v_cmp_ge_f32_e64 s[8:9], 0, v86
	s_nop 1
	v_cndmask_b32_e64 v83, v83, v84, s[8:9]
	v_cmp_lt_f32_e64 s[8:9], 0, v87
	s_nop 1
	v_cndmask_b32_e64 v83, v83, v85, s[8:9]
	v_mul_f32_e32 v84, 0x37800000, v83
	v_cndmask_b32_e32 v83, v83, v84, vcc
	v_cmp_class_f32_e32 vcc, v82, v213
	v_lshlrev_b64 v[84:85], 13, v[98:99]
	s_nop 0
	v_cndmask_b32_e32 v82, v83, v82, vcc
	v_div_scale_f32 v83, s[8:9], v82, v82, 1.0
	v_rcp_f32_e32 v86, v83
	v_div_scale_f32 v87, vcc, 1.0, v82, 1.0
	v_fma_f32 v88, -v83, v86, 1.0
	v_fmac_f32_e32 v86, v88, v86
	v_mul_f32_e32 v88, v87, v86
	v_fma_f32 v89, -v83, v88, v87
	v_fmac_f32_e32 v88, v89, v86
	v_fma_f32 v83, -v83, v88, v87
	v_div_fmas_f32 v83, v83, v86, v88
	v_div_fixup_f32 v82, v83, v82, 1.0
	v_pk_mul_f32 v[80:81], v[80:81], v[82:83] op_sel_hi:[1,0]
	v_pk_mul_f32 v[78:79], v[78:79], v[82:83] op_sel_hi:[1,0]
	v_pk_mul_f32 v[76:77], v[76:77], v[82:83] op_sel_hi:[1,0]
	v_pk_mul_f32 v[74:75], v[74:75], v[82:83] op_sel_hi:[1,0]
	v_max_f32_e32 v78, 0, v78
	v_max_f32_e32 v74, 0, v74
	v_max_f32_e32 v79, 0, v79
	v_max_f32_e32 v75, 0, v75
	v_max_f32_e32 v80, 0, v80
	v_max_f32_e32 v76, 0, v76
	v_max_f32_e32 v81, 0, v81
	v_max_f32_e32 v77, 0, v77
	v_mul_f32_e32 v78, v78, v78
	v_mul_f32_e32 v83, v74, v74
	v_mul_f32_e32 v74, v79, v79
	v_mul_f32_e32 v79, v75, v75
	v_mul_f32_e32 v75, v80, v80
	v_mul_f32_e32 v80, v76, v76
	v_mul_f32_e32 v76, v81, v81
	v_mul_f32_e32 v77, v77, v77
	v_cvt_pk_bf16_f32 v74, v78, v74
	v_cvt_pk_bf16_f32 v75, v75, v76
	v_cvt_pk_bf16_f32 v76, v83, v79
	v_lshl_add_u64 v[78:79], s[40:41], 0, v[84:85]
	v_cvt_pk_bf16_f32 v77, v80, v77
	s_and_saveexec_b64 s[8:9], s[4:5]
	s_cbranch_execz .LBB0_2445
	v_lshl_add_u64 v[80:81], v[140:141], 1, v[78:79]
	global_store_dwordx4 v[80:81], v[74:77], off nt

.LBB0_2447:
	s_or_b64 exec, exec, s[8:9]
	v_add_u32_e32 v82, 0x80, v142
	v_ashrrev_i32_e32 v83, 31, v82
	v_lshlrev_b64 v[66:67], 6, v[82:83]
	v_lshl_add_u64 v[78:79], s[18:19], 0, v[66:67]
	global_load_dwordx4 v[220:223], v[250:251], off offset:1024
	s_waitcnt vmcnt(3)
	v_add_f32_e32 v216, v216, v217
	v_add_f32_e32 v218, v218, v219
	v_add_f32_e32 v216, v216, v218
	v_mov_b32_e32 v252, v216
	s_nop 1
	v_permlane16_swap_b32_e32 v252, v216
	v_add_f32_e32 v216, v216, v252
	v_mov_b32_e32 v252, v216
	s_nop 1
	v_permlane32_swap_b32_e32 v252, v216
	v_add_f32_e32 v66, v216, v252
	v_fmamk_f32 v66, v66, 0x3a800000, v212
	v_mul_f32_e32 v67, 0x4f800000, v66
	v_cmp_gt_f32_e32 vcc, s74, v66
	s_nop 1
	v_cndmask_b32_e32 v66, v66, v67, vcc
	v_sqrt_f32_e32 v67, v66
	s_nop 0
	v_add_u32_e32 v68, -1, v67
	v_add_u32_e32 v69, 1, v67
	v_fma_f32 v70, -v68, v67, v66
	v_fma_f32 v71, -v69, v67, v66
	v_cmp_ge_f32_e64 s[8:9], 0, v70
	s_nop 1
	v_cndmask_b32_e64 v67, v67, v68, s[8:9]
	v_cmp_lt_f32_e64 s[8:9], 0, v71
	s_nop 1
	v_cndmask_b32_e64 v67, v67, v69, s[8:9]
	v_mul_f32_e32 v68, 0x37800000, v67
	v_cndmask_b32_e32 v67, v67, v68, vcc
	v_cmp_class_f32_e32 vcc, v66, v213
	v_lshlrev_b64 v[68:69], 13, v[82:83]
	s_nop 0
	v_cndmask_b32_e32 v66, v67, v66, vcc
	v_div_scale_f32 v67, s[8:9], v66, v66, 1.0
	v_rcp_f32_e32 v70, v67
	v_div_scale_f32 v71, vcc, 1.0, v66, 1.0
	v_fma_f32 v72, -v67, v70, 1.0
	v_fmac_f32_e32 v70, v72, v70
	v_mul_f32_e32 v72, v71, v70
	v_fma_f32 v73, -v67, v72, v71
	v_fmac_f32_e32 v72, v73, v70
	v_fma_f32 v67, -v67, v72, v71
	v_div_fmas_f32 v67, v67, v70, v72
	v_div_fixup_f32 v66, v67, v66, 1.0
	v_pk_mul_f32 v[64:65], v[64:65], v[66:67] op_sel_hi:[1,0]
	v_pk_mul_f32 v[62:63], v[62:63], v[66:67] op_sel_hi:[1,0]
	v_pk_mul_f32 v[60:61], v[60:61], v[66:67] op_sel_hi:[1,0]
	v_pk_mul_f32 v[58:59], v[58:59], v[66:67] op_sel_hi:[1,0]
	v_max_f32_e32 v62, 0, v62
	v_max_f32_e32 v58, 0, v58
	v_max_f32_e32 v63, 0, v63
	v_max_f32_e32 v59, 0, v59
	v_max_f32_e32 v64, 0, v64
	v_max_f32_e32 v60, 0, v60
	v_max_f32_e32 v65, 0, v65
	v_max_f32_e32 v61, 0, v61
	v_mul_f32_e32 v62, v62, v62
	v_mul_f32_e32 v67, v58, v58
	v_mul_f32_e32 v58, v63, v63
	v_mul_f32_e32 v63, v59, v59
	v_mul_f32_e32 v59, v64, v64
	v_mul_f32_e32 v64, v60, v60
	v_mul_f32_e32 v60, v65, v65
	v_mul_f32_e32 v61, v61, v61
	v_cvt_pk_bf16_f32 v58, v62, v58
	v_cvt_pk_bf16_f32 v59, v59, v60
	v_cvt_pk_bf16_f32 v60, v67, v63
	v_lshl_add_u64 v[62:63], s[40:41], 0, v[68:69]
	v_cvt_pk_bf16_f32 v61, v64, v61
	s_and_saveexec_b64 s[8:9], s[4:5]
	s_cbranch_execz .LBB0_2449
	v_lshl_add_u64 v[64:65], v[140:141], 1, v[62:63]
	global_store_dwordx4 v[64:65], v[58:61], off nt

.LBB0_2451:
	s_or_b64 exec, exec, s[8:9]
	v_add_u32_e32 v66, 0x90, v142
	v_ashrrev_i32_e32 v67, 31, v66
	v_lshlrev_b64 v[50:51], 6, v[66:67]
	v_lshl_add_u64 v[62:63], s[18:19], 0, v[50:51]
	global_load_dwordx4 v[216:219], v[250:251], off offset:2048
	s_waitcnt vmcnt(3)
	v_add_f32_e32 v220, v220, v221
	v_add_f32_e32 v222, v222, v223
	v_add_f32_e32 v220, v220, v222
	v_mov_b32_e32 v252, v220
	s_nop 1
	v_permlane16_swap_b32_e32 v252, v220
	v_add_f32_e32 v220, v220, v252
	v_mov_b32_e32 v252, v220
	s_nop 1
	v_permlane32_swap_b32_e32 v252, v220
	v_add_f32_e32 v50, v220, v252
	v_fmamk_f32 v50, v50, 0x3a800000, v212
	v_mul_f32_e32 v51, 0x4f800000, v50
	v_cmp_gt_f32_e32 vcc, s74, v50
	s_nop 1
	v_cndmask_b32_e32 v50, v50, v51, vcc
	v_sqrt_f32_e32 v51, v50
	s_nop 0
	v_add_u32_e32 v52, -1, v51
	v_add_u32_e32 v53, 1, v51
	v_fma_f32 v54, -v52, v51, v50
	v_fma_f32 v55, -v53, v51, v50
	v_cmp_ge_f32_e64 s[8:9], 0, v54
	s_nop 1
	v_cndmask_b32_e64 v51, v51, v52, s[8:9]
	v_cmp_lt_f32_e64 s[8:9], 0, v55
	s_nop 1
	v_cndmask_b32_e64 v51, v51, v53, s[8:9]
	v_mul_f32_e32 v52, 0x37800000, v51
	v_cndmask_b32_e32 v51, v51, v52, vcc
	v_cmp_class_f32_e32 vcc, v50, v213
	v_lshlrev_b64 v[52:53], 13, v[66:67]
	s_nop 0
	v_cndmask_b32_e32 v50, v51, v50, vcc
	v_div_scale_f32 v51, s[8:9], v50, v50, 1.0
	v_rcp_f32_e32 v54, v51
	v_div_scale_f32 v55, vcc, 1.0, v50, 1.0
	v_fma_f32 v56, -v51, v54, 1.0
	v_fmac_f32_e32 v54, v56, v54
	v_mul_f32_e32 v56, v55, v54
	v_fma_f32 v57, -v51, v56, v55
	v_fmac_f32_e32 v56, v57, v54
	v_fma_f32 v51, -v51, v56, v55
	v_div_fmas_f32 v51, v51, v54, v56
	v_div_fixup_f32 v50, v51, v50, 1.0
	v_pk_mul_f32 v[48:49], v[48:49], v[50:51] op_sel_hi:[1,0]
	v_pk_mul_f32 v[46:47], v[46:47], v[50:51] op_sel_hi:[1,0]
	v_pk_mul_f32 v[44:45], v[44:45], v[50:51] op_sel_hi:[1,0]
	v_pk_mul_f32 v[42:43], v[42:43], v[50:51] op_sel_hi:[1,0]
	v_max_f32_e32 v46, 0, v46
	v_max_f32_e32 v42, 0, v42
	v_max_f32_e32 v47, 0, v47
	v_max_f32_e32 v43, 0, v43
	v_max_f32_e32 v48, 0, v48
	v_max_f32_e32 v44, 0, v44
	v_max_f32_e32 v49, 0, v49
	v_max_f32_e32 v45, 0, v45
	v_mul_f32_e32 v46, v46, v46
	v_mul_f32_e32 v51, v42, v42
	v_mul_f32_e32 v42, v47, v47
	v_mul_f32_e32 v47, v43, v43
	v_mul_f32_e32 v43, v48, v48
	v_mul_f32_e32 v48, v44, v44
	v_mul_f32_e32 v44, v49, v49
	v_mul_f32_e32 v45, v45, v45
	v_cvt_pk_bf16_f32 v42, v46, v42
	v_cvt_pk_bf16_f32 v43, v43, v44
	v_cvt_pk_bf16_f32 v44, v51, v47
	v_lshl_add_u64 v[46:47], s[40:41], 0, v[52:53]
	v_cvt_pk_bf16_f32 v45, v48, v45
	s_and_saveexec_b64 s[8:9], s[4:5]
	s_cbranch_execz .LBB0_2453
	v_lshl_add_u64 v[48:49], v[140:141], 1, v[46:47]
	global_store_dwordx4 v[48:49], v[42:45], off nt

.LBB0_2455:
	s_or_b64 exec, exec, s[8:9]
	v_add_u32_e32 v50, 0xa0, v142
	v_ashrrev_i32_e32 v51, 31, v50
	v_lshlrev_b64 v[34:35], 6, v[50:51]
	v_lshl_add_u64 v[46:47], s[18:19], 0, v[34:35]
	global_load_dwordx4 v[220:223], v[250:251], off offset:3072
	s_waitcnt vmcnt(3)
	v_add_f32_e32 v216, v216, v217
	v_add_f32_e32 v218, v218, v219
	v_add_f32_e32 v216, v216, v218
	v_mov_b32_e32 v252, v216
	s_nop 1
	v_permlane16_swap_b32_e32 v252, v216
	v_add_f32_e32 v216, v216, v252
	v_mov_b32_e32 v252, v216
	s_nop 1
	v_permlane32_swap_b32_e32 v252, v216
	v_add_f32_e32 v34, v216, v252
	v_fmamk_f32 v34, v34, 0x3a800000, v212
	v_mul_f32_e32 v35, 0x4f800000, v34
	v_cmp_gt_f32_e32 vcc, s74, v34
	s_nop 1
	v_cndmask_b32_e32 v34, v34, v35, vcc
	v_sqrt_f32_e32 v35, v34
	s_nop 0
	v_add_u32_e32 v36, -1, v35
	v_add_u32_e32 v37, 1, v35
	v_fma_f32 v38, -v36, v35, v34
	v_fma_f32 v39, -v37, v35, v34
	v_cmp_ge_f32_e64 s[8:9], 0, v38
	s_nop 1
	v_cndmask_b32_e64 v35, v35, v36, s[8:9]
	v_cmp_lt_f32_e64 s[8:9], 0, v39
	s_nop 1
	v_cndmask_b32_e64 v35, v35, v37, s[8:9]
	v_mul_f32_e32 v36, 0x37800000, v35
	v_cndmask_b32_e32 v35, v35, v36, vcc
	v_cmp_class_f32_e32 vcc, v34, v213
	v_lshlrev_b64 v[36:37], 13, v[50:51]
	s_nop 0
	v_cndmask_b32_e32 v34, v35, v34, vcc
	v_div_scale_f32 v35, s[8:9], v34, v34, 1.0
	v_rcp_f32_e32 v38, v35
	v_div_scale_f32 v39, vcc, 1.0, v34, 1.0
	v_fma_f32 v40, -v35, v38, 1.0
	v_fmac_f32_e32 v38, v40, v38
	v_mul_f32_e32 v40, v39, v38
	v_fma_f32 v41, -v35, v40, v39
	v_fmac_f32_e32 v40, v41, v38
	v_fma_f32 v35, -v35, v40, v39
	v_div_fmas_f32 v35, v35, v38, v40
	v_div_fixup_f32 v34, v35, v34, 1.0
	v_pk_mul_f32 v[32:33], v[32:33], v[34:35] op_sel_hi:[1,0]
	v_pk_mul_f32 v[30:31], v[30:31], v[34:35] op_sel_hi:[1,0]
	v_pk_mul_f32 v[28:29], v[28:29], v[34:35] op_sel_hi:[1,0]
	v_pk_mul_f32 v[26:27], v[26:27], v[34:35] op_sel_hi:[1,0]
	v_max_f32_e32 v30, 0, v30
	v_max_f32_e32 v26, 0, v26
	v_max_f32_e32 v31, 0, v31
	v_max_f32_e32 v27, 0, v27
	v_max_f32_e32 v32, 0, v32
	v_max_f32_e32 v28, 0, v28
	v_max_f32_e32 v33, 0, v33
	v_max_f32_e32 v29, 0, v29
	v_mul_f32_e32 v30, v30, v30
	v_mul_f32_e32 v35, v26, v26
	v_mul_f32_e32 v26, v31, v31
	v_mul_f32_e32 v31, v27, v27
	v_mul_f32_e32 v27, v32, v32
	v_mul_f32_e32 v32, v28, v28
	v_mul_f32_e32 v28, v33, v33
	v_mul_f32_e32 v29, v29, v29
	v_cvt_pk_bf16_f32 v26, v30, v26
	v_cvt_pk_bf16_f32 v27, v27, v28
	v_cvt_pk_bf16_f32 v28, v35, v31
	v_lshl_add_u64 v[30:31], s[40:41], 0, v[36:37]
	v_cvt_pk_bf16_f32 v29, v32, v29
	s_and_saveexec_b64 s[8:9], s[4:5]
	s_cbranch_execz .LBB0_2457
	v_lshl_add_u64 v[32:33], v[140:141], 1, v[30:31]
	global_store_dwordx4 v[32:33], v[26:29], off nt

.LBB0_2459:
	s_or_b64 exec, exec, s[8:9]
	v_add_u32_e32 v34, 0xb0, v142
	v_ashrrev_i32_e32 v35, 31, v34
	v_lshlrev_b64 v[18:19], 6, v[34:35]
	v_lshl_add_u64 v[30:31], s[18:19], 0, v[18:19]
	s_waitcnt vmcnt(2)
	v_add_f32_e32 v220, v220, v221
	v_add_f32_e32 v222, v222, v223
	v_add_f32_e32 v220, v220, v222
	v_mov_b32_e32 v252, v220
	s_nop 1
	v_permlane16_swap_b32_e32 v252, v220
	v_add_f32_e32 v220, v220, v252
	v_mov_b32_e32 v252, v220
	s_nop 1
	v_permlane32_swap_b32_e32 v252, v220
	v_add_f32_e32 v18, v220, v252
	v_fmamk_f32 v18, v18, 0x3a800000, v212
	v_mul_f32_e32 v19, 0x4f800000, v18
	v_cmp_gt_f32_e32 vcc, s74, v18
	s_nop 1
	v_cndmask_b32_e32 v18, v18, v19, vcc
	v_sqrt_f32_e32 v19, v18
	s_nop 0
	v_add_u32_e32 v20, -1, v19
	v_add_u32_e32 v21, 1, v19
	v_fma_f32 v22, -v20, v19, v18
	v_fma_f32 v23, -v21, v19, v18
	v_cmp_ge_f32_e64 s[8:9], 0, v22
	s_nop 1
	v_cndmask_b32_e64 v19, v19, v20, s[8:9]
	v_cmp_lt_f32_e64 s[8:9], 0, v23
	s_nop 1
	v_cndmask_b32_e64 v19, v19, v21, s[8:9]
	v_mul_f32_e32 v20, 0x37800000, v19
	v_cndmask_b32_e32 v19, v19, v20, vcc
	v_cmp_class_f32_e32 vcc, v18, v213
	v_lshlrev_b64 v[20:21], 13, v[34:35]
	s_nop 0
	v_cndmask_b32_e32 v18, v19, v18, vcc
	v_div_scale_f32 v19, s[8:9], v18, v18, 1.0
	v_rcp_f32_e32 v22, v19
	v_div_scale_f32 v23, vcc, 1.0, v18, 1.0
	v_fma_f32 v24, -v19, v22, 1.0
	v_fmac_f32_e32 v22, v24, v22
	v_mul_f32_e32 v24, v23, v22
	v_fma_f32 v25, -v19, v24, v23
	v_fmac_f32_e32 v24, v25, v22
	v_fma_f32 v19, -v19, v24, v23
	v_div_fmas_f32 v19, v19, v22, v24
	v_div_fixup_f32 v18, v19, v18, 1.0
	v_pk_mul_f32 v[16:17], v[16:17], v[18:19] op_sel_hi:[1,0]
	v_pk_mul_f32 v[14:15], v[14:15], v[18:19] op_sel_hi:[1,0]
	v_pk_mul_f32 v[12:13], v[12:13], v[18:19] op_sel_hi:[1,0]
	v_pk_mul_f32 v[10:11], v[10:11], v[18:19] op_sel_hi:[1,0]
	v_max_f32_e32 v14, 0, v14
	v_max_f32_e32 v10, 0, v10
	v_max_f32_e32 v15, 0, v15
	v_max_f32_e32 v11, 0, v11
	v_max_f32_e32 v16, 0, v16
	v_max_f32_e32 v12, 0, v12
	v_max_f32_e32 v17, 0, v17
	v_max_f32_e32 v13, 0, v13
	v_mul_f32_e32 v14, v14, v14
	v_mul_f32_e32 v19, v10, v10
	v_mul_f32_e32 v10, v15, v15
	v_mul_f32_e32 v15, v11, v11
	v_mul_f32_e32 v11, v16, v16
	v_mul_f32_e32 v16, v12, v12
	v_mul_f32_e32 v12, v17, v17
	v_mul_f32_e32 v13, v13, v13
	v_cvt_pk_bf16_f32 v10, v14, v10
	v_cvt_pk_bf16_f32 v11, v11, v12
	v_cvt_pk_bf16_f32 v12, v19, v15
	v_lshl_add_u64 v[14:15], s[40:41], 0, v[20:21]
	v_cvt_pk_bf16_f32 v13, v16, v13
	s_and_saveexec_b64 s[8:9], s[4:5]
	s_cbranch_execz .LBB0_2461
	v_lshl_add_u64 v[16:17], v[140:141], 1, v[14:15]
	global_store_dwordx4 v[16:17], v[10:13], off nt

	.amdhsa_kernel _Z14fwd_megakernel4Args
		.amdhsa_group_segment_fixed_size 0
		.amdhsa_private_segment_fixed_size 0
		.amdhsa_kernarg_size 552
		.amdhsa_user_sgpr_count 2
		.amdhsa_user_sgpr_dispatch_ptr 0
		.amdhsa_user_sgpr_queue_ptr 0
		.amdhsa_user_sgpr_kernarg_segment_ptr 1
		.amdhsa_user_sgpr_dispatch_id 0
		.amdhsa_user_sgpr_kernarg_preload_length 0
		.amdhsa_user_sgpr_kernarg_preload_offset 0
		.amdhsa_user_sgpr_private_segment_size 0
		.amdhsa_uses_dynamic_stack 0
		.amdhsa_enable_private_segment 0
		.amdhsa_system_sgpr_workgroup_id_x 1
		.amdhsa_system_sgpr_workgroup_id_y 0
		.amdhsa_system_sgpr_workgroup_id_z 0
		.amdhsa_system_sgpr_workgroup_info 0
		.amdhsa_system_vgpr_workitem_id 2
		.amdhsa_next_free_vgpr 256
		.amdhsa_next_free_sgpr 102
		.amdhsa_accum_offset 256
		.amdhsa_reserve_vcc 1
		.amdhsa_float_round_mode_32 0
		.amdhsa_float_round_mode_16_64 0
		.amdhsa_float_denorm_mode_32 3
		.amdhsa_float_denorm_mode_16_64 3
		.amdhsa_dx10_clamp 1
		.amdhsa_ieee_mode 1
		.amdhsa_fp16_overflow 0
		.amdhsa_tg_split 0
		.amdhsa_exception_fp_ieee_invalid_op 0
		.amdhsa_exception_fp_denorm_src 0
		.amdhsa_exception_fp_ieee_div_zero 0
		.amdhsa_exception_fp_ieee_overflow 0
		.amdhsa_exception_fp_ieee_underflow 0
		.amdhsa_exception_fp_ieee_inexact 0
		.amdhsa_exception_int_div_zero 0
	.end_amdhsa_kernel

amdhsa.kernels:
  - .agpr_count:     0
    .args:
      - .offset:         0
        .size:           296
        .value_kind:     by_value
      - .offset:         296
        .size:           4
        .value_kind:     hidden_block_count_x
      - .offset:         300
        .size:           4
        .value_kind:     hidden_block_count_y
      - .offset:         304
        .size:           4
        .value_kind:     hidden_block_count_z
      - .offset:         308
        .size:           2
        .value_kind:     hidden_group_size_x
      - .offset:         310
        .size:           2
        .value_kind:     hidden_group_size_y
      - .offset:         312
        .size:           2
        .value_kind:     hidden_group_size_z
      - .offset:         314
        .size:           2
        .value_kind:     hidden_remainder_x
      - .offset:         316
        .size:           2
        .value_kind:     hidden_remainder_y
      - .offset:         318
        .size:           2
        .value_kind:     hidden_remainder_z
      - .offset:         336
        .size:           8
        .value_kind:     hidden_global_offset_x
      - .offset:         344
        .size:           8
        .value_kind:     hidden_global_offset_y
      - .offset:         352
        .size:           8
        .value_kind:     hidden_global_offset_z
      - .offset:         360
        .size:           2
        .value_kind:     hidden_grid_dims
      - .offset:         384
        .size:           8
        .value_kind:     hidden_multigrid_sync_arg
      - .offset:         416
        .size:           4
        .value_kind:     hidden_dynamic_lds_size
    .group_segment_fixed_size: 0
    .kernarg_segment_align: 8
    .kernarg_segment_size: 552
    .language:       OpenCL C
    .language_version:
      - 2
      - 0
    .max_flat_workgroup_size: 512
    .name:           _Z14fwd_megakernel4Args
    .private_segment_fixed_size: 0
    .sgpr_count:     108
    .sgpr_spill_count: 3
    .symbol:         _Z14fwd_megakernel4Args.kd
    .uniform_work_group_size: 1
    .uses_dynamic_stack: false
    .vgpr_count:     256
    .vgpr_spill_count: 0
    .wavefront_size: 64
